# attention sink load hoisted to unit top; FFT context-conv edge loads issued together (no per-load vmcnt drain)
# baseline (speedup 1.0000x reference)
.LBB0_410:
	s_or_b64 exec, exec, s[88:89]
	v_lshlrev_b32_e32 v66, 1, v8
	v_lshl_add_u64 v[6:7], v[6:7], 0, v[66:67]
	v_lshl_add_u64 v[2:3], v[2:3], 0, v[66:67]
	global_load_ushort v6, v[6:7], off
	s_nop 0
	global_load_ushort v7, v[2:3], off
	s_waitcnt vmcnt(2)
	v_lshlrev_b32_e32 v4, 16, v244
	v_lshlrev_b32_e32 v0, 16, v245
	v_lshlrev_b32_e32 v5, 16, v246
	v_lshlrev_b32_e32 v1, 16, v247
	v_pk_fma_f32 v[2:3], v[84:85], v[4:5], v[90:91]
	v_add_u32_e32 v8, 0x200, v11
	v_cmp_lt_i32_e32 vcc, s27, v11
	s_or_b64 s[86:87], vcc, s[86:87]
	v_mov_b32_e32 v11, v8
	s_waitcnt vmcnt(1)
	v_lshlrev_b32_e32 v5, 16, v6
	s_waitcnt vmcnt(0)
	v_lshlrev_b32_e32 v4, 16, v7
	v_pk_fma_f32 v[2:3], v[86:87], v[4:5], v[2:3]
	s_nop 0
	v_pk_fma_f32 v[0:1], v[88:89], v[0:1], v[2:3]
	s_nop 0
	v_mul_f32_e32 v0, v0, v1
	ds_write_b32 v10, v0
	v_add_u32_e32 v10, 0x800, v10
	s_andn2_b64 exec, exec, s[86:87]
	s_cbranch_execz .LBB0_419
.LBB0_411:
	v_and_b32_e32 v6, 0xffffff00, v11
	v_ashrrev_i32_e32 v7, 31, v6
	v_lshl_add_u64 v[2:3], v[6:7], 1, s[44:45]
	v_mov_b32_e32 v0, 0
	v_lshlrev_b32_e32 v66, 1, v64
	v_mov_b32_e32 v4, 0
	v_mov_b32_e32 v244, 0
	s_and_saveexec_b64 s[88:89], s[20:21]
	s_cbranch_execz .LBB0_413
	v_lshl_add_u64 v[4:5], v[2:3], 0, v[66:67]
	global_load_ushort v244, v[4:5], off offset:-2
	s_nop 0
	s_nop 0
.LBB0_413:
	s_or_b64 exec, exec, s[88:89]
	v_mov_b32_e32 v245, 0
	s_and_saveexec_b64 s[88:89], s[22:23]
	s_cbranch_execz .LBB0_415
	v_lshl_add_u64 v[0:1], v[2:3], 0, v[66:67]
	global_load_ushort v245, v[0:1], off offset:2
	s_nop 0
	s_nop 0
.LBB0_415:
	s_or_b64 exec, exec, s[88:89]
	v_lshl_add_u64 v[6:7], v[6:7], 1, s[58:59]
	v_mov_b32_e32 v1, 0
	v_mov_b32_e32 v5, 0
	v_mov_b32_e32 v246, 0
	s_and_saveexec_b64 s[88:89], s[20:21]
	s_cbranch_execz .LBB0_417
	v_lshl_add_u64 v[8:9], v[6:7], 0, v[66:67]
	global_load_ushort v246, v[8:9], off offset:-2
	s_nop 0
	s_nop 0
.LBB0_417:
	s_or_b64 exec, exec, s[88:89]
	v_mov_b64_e32 v[8:9], 0xff
	v_mov_b32_e32 v247, 0
	s_and_saveexec_b64 s[88:89], s[22:23]
	s_cbranch_execz .LBB0_410
	v_lshl_add_u64 v[8:9], v[6:7], 0, v[66:67]
	global_load_ushort v247, v[8:9], off offset:2
	v_mov_b64_e32 v[8:9], v[64:65]
	s_nop 0
	s_nop 0
	s_branch .LBB0_410

.LBB0_1166:
	v_readlane_b32 s12, v243, 21
	v_readlane_b32 s13, v243, 22
	v_readlane_b32 s16, v243, 25
	v_readlane_b32 s17, v243, 26
	v_readlane_b32 s20, v243, 29
	v_readlane_b32 s21, v243, 30
	v_ashrrev_i32_e32 v165, 31, v164
	s_mov_b64 s[12:13], s[16:17]
	s_mov_b64 s[16:17], s[20:21]
	v_lshl_add_u64 v[80:81], v[164:165], 2, s[16:17]
	v_mov_b32_e32 v80, v240
	ds_bpermute_b32 v82, v202, v188
	v_readlane_b32 s11, v243, 60
	v_readlane_b32 s6, v243, 50
	v_readlane_b32 s7, v243, 51
	v_readlane_b32 s14, v243, 23
	s_waitcnt lgkmcnt(0)
	v_add_f32_e32 v82, v188, v82
	v_readlane_b32 s15, v243, 24
	v_readlane_b32 s18, v243, 27
	v_readlane_b32 s19, v243, 28
	v_readlane_b32 s22, v243, 31
	v_readlane_b32 s23, v243, 32
	v_readlane_b32 s24, v243, 33
	v_readlane_b32 s25, v243, 34
	v_readlane_b32 s26, v243, 35
	v_readlane_b32 s27, v243, 36
	s_waitcnt vmcnt(0)
	v_fmamk_f32 v80, v80, 0x3fb8aa3b, v0
	v_exp_f32_e32 v83, v80
	v_lshl_add_u64 v[80:81], v[162:163], 1, v[154:155]
	v_add_f32_e32 v82, v83, v82
	v_div_scale_f32 v84, s[0:1], v82, v82, 1.0
	v_rcp_f32_e32 v85, v84
	s_nop 0
	v_fma_f32 v86, -v84, v85, 1.0
	v_fmac_f32_e32 v85, v86, v85
	v_div_scale_f32 v86, vcc, 1.0, v82, 1.0
	v_mul_f32_e32 v87, v86, v85
	v_fma_f32 v88, -v84, v87, v86
	v_fmac_f32_e32 v87, v88, v85
	v_fma_f32 v84, -v84, v87, v86
	v_div_fmas_f32 v84, v84, v85, v87
	v_div_fixup_f32 v82, v84, v82, 1.0
	v_lshlrev_b64 v[84:85], 11, v[160:161]
	v_pk_mul_f32 v[48:49], v[48:49], v[82:83] op_sel_hi:[1,0]
	v_pk_mul_f32 v[50:51], v[50:51], v[82:83] op_sel_hi:[1,0]
	v_lshl_add_u64 v[84:85], v[80:81], 0, v[84:85]
	v_cvt_pk_bf16_f32 v48, v48, v49
	v_cvt_pk_bf16_f32 v49, v50, v51
	global_store_dwordx2 v[84:85], v[48:49], off offset:64
	v_pk_mul_f32 v[48:49], v[52:53], v[82:83] op_sel_hi:[1,0]
	v_pk_mul_f32 v[50:51], v[54:55], v[82:83] op_sel_hi:[1,0]
	v_cvt_pk_bf16_f32 v48, v48, v49
	v_cvt_pk_bf16_f32 v49, v50, v51
	global_store_dwordx2 v[84:85], v[48:49], off offset:80
	v_pk_mul_f32 v[48:49], v[56:57], v[82:83] op_sel_hi:[1,0]
	v_pk_mul_f32 v[50:51], v[58:59], v[82:83] op_sel_hi:[1,0]
	v_cvt_pk_bf16_f32 v48, v48, v49
	v_cvt_pk_bf16_f32 v49, v50, v51
	global_store_dwordx2 v[84:85], v[48:49], off offset:96
	v_pk_mul_f32 v[48:49], v[60:61], v[82:83] op_sel_hi:[1,0]
	v_pk_mul_f32 v[50:51], v[62:63], v[82:83] op_sel_hi:[1,0]
	v_cvt_pk_bf16_f32 v48, v48, v49
	v_cvt_pk_bf16_f32 v49, v50, v51
	global_store_dwordx2 v[84:85], v[48:49], off offset:112
	ds_bpermute_b32 v48, v202, v187
	v_pk_mul_f32 v[64:65], v[64:65], v[82:83] op_sel_hi:[1,0]
	v_pk_mul_f32 v[66:67], v[66:67], v[82:83] op_sel_hi:[1,0]
	v_cvt_pk_bf16_f32 v64, v64, v65
	v_cvt_pk_bf16_f32 v65, v66, v67
	s_waitcnt lgkmcnt(0)
	v_add_f32_e32 v48, v187, v48
	v_add_f32_e32 v48, v83, v48
	v_div_scale_f32 v49, s[0:1], v48, v48, 1.0
	v_rcp_f32_e32 v50, v49
	global_store_dwordx2 v[84:85], v[64:65], off
	v_pk_mul_f32 v[64:65], v[68:69], v[82:83] op_sel_hi:[1,0]
	v_pk_mul_f32 v[66:67], v[70:71], v[82:83] op_sel_hi:[1,0]
	v_fma_f32 v51, -v49, v50, 1.0
	v_fmac_f32_e32 v50, v51, v50
	v_div_scale_f32 v51, vcc, 1.0, v48, 1.0
	v_mul_f32_e32 v52, v51, v50
	v_fma_f32 v53, -v49, v52, v51
	v_fmac_f32_e32 v52, v53, v50
	v_fma_f32 v49, -v49, v52, v51
	v_div_fmas_f32 v49, v49, v50, v52
	v_div_fixup_f32 v48, v49, v48, 1.0
	v_lshlrev_b64 v[50:51], 11, v[166:167]
	v_pk_mul_f32 v[32:33], v[32:33], v[48:49] op_sel_hi:[1,0]
	v_pk_mul_f32 v[34:35], v[34:35], v[48:49] op_sel_hi:[1,0]
	v_pk_mul_f32 v[16:17], v[16:17], v[48:49] op_sel_hi:[1,0]
	v_pk_mul_f32 v[18:19], v[18:19], v[48:49] op_sel_hi:[1,0]
	v_lshl_add_u64 v[50:51], v[80:81], 0, v[50:51]
	v_cvt_pk_bf16_f32 v32, v32, v33
	v_cvt_pk_bf16_f32 v33, v34, v35
	v_cvt_pk_bf16_f32 v16, v16, v17
	v_cvt_pk_bf16_f32 v17, v18, v19
	global_store_dwordx2 v[50:51], v[32:33], off
	v_pk_mul_f32 v[32:33], v[36:37], v[48:49] op_sel_hi:[1,0]
	v_pk_mul_f32 v[34:35], v[38:39], v[48:49] op_sel_hi:[1,0]
	global_store_dwordx2 v[50:51], v[16:17], off offset:64
	v_pk_mul_f32 v[16:17], v[20:21], v[48:49] op_sel_hi:[1,0]
	v_pk_mul_f32 v[18:19], v[22:23], v[48:49] op_sel_hi:[1,0]
	v_cvt_pk_bf16_f32 v64, v64, v65
	v_cvt_pk_bf16_f32 v65, v66, v67
	v_cvt_pk_bf16_f32 v32, v32, v33
	v_cvt_pk_bf16_f32 v33, v34, v35
	v_cvt_pk_bf16_f32 v16, v16, v17
	v_cvt_pk_bf16_f32 v17, v18, v19
	global_store_dwordx2 v[84:85], v[64:65], off offset:16
	v_pk_mul_f32 v[64:65], v[72:73], v[82:83] op_sel_hi:[1,0]
	v_pk_mul_f32 v[66:67], v[74:75], v[82:83] op_sel_hi:[1,0]
	global_store_dwordx2 v[50:51], v[32:33], off offset:16
	v_pk_mul_f32 v[32:33], v[40:41], v[48:49] op_sel_hi:[1,0]
	v_pk_mul_f32 v[34:35], v[42:43], v[48:49] op_sel_hi:[1,0]
	global_store_dwordx2 v[50:51], v[16:17], off offset:80
	v_pk_mul_f32 v[16:17], v[24:25], v[48:49] op_sel_hi:[1,0]
	v_pk_mul_f32 v[18:19], v[26:27], v[48:49] op_sel_hi:[1,0]
	v_readlane_b32 s0, v243, 1
	v_cvt_pk_bf16_f32 v64, v64, v65
	v_cvt_pk_bf16_f32 v65, v66, v67
	v_cvt_pk_bf16_f32 v32, v32, v33
	v_cvt_pk_bf16_f32 v33, v34, v35
	v_cvt_pk_bf16_f32 v16, v16, v17
	v_cvt_pk_bf16_f32 v17, v18, v19
	v_readlane_b32 s2, v243, 3
	global_store_dwordx2 v[84:85], v[64:65], off offset:32
	v_pk_mul_f32 v[64:65], v[76:77], v[82:83] op_sel_hi:[1,0]
	v_pk_mul_f32 v[66:67], v[78:79], v[82:83] op_sel_hi:[1,0]
	global_store_dwordx2 v[50:51], v[32:33], off offset:32
	v_pk_mul_f32 v[32:33], v[44:45], v[48:49] op_sel_hi:[1,0]
	v_pk_mul_f32 v[34:35], v[46:47], v[48:49] op_sel_hi:[1,0]
	global_store_dwordx2 v[50:51], v[16:17], off offset:96
	v_pk_mul_f32 v[16:17], v[28:29], v[48:49] op_sel_hi:[1,0]
	v_pk_mul_f32 v[18:19], v[30:31], v[48:49] op_sel_hi:[1,0]
	s_add_i32 s11, s11, s2
	v_cvt_pk_bf16_f32 v64, v64, v65
	v_cvt_pk_bf16_f32 v65, v66, v67
	v_cvt_pk_bf16_f32 v32, v32, v33
	v_cvt_pk_bf16_f32 v33, v34, v35
	v_cvt_pk_bf16_f32 v16, v16, v17
	v_cvt_pk_bf16_f32 v17, v18, v19
	s_cmpk_gt_i32 s11, 0x7ff
	global_store_dwordx2 v[84:85], v[64:65], off offset:48
	global_store_dwordx2 v[50:51], v[32:33], off offset:48
	global_store_dwordx2 v[50:51], v[16:17], off offset:112
	v_readlane_b32 s1, v243, 2
	v_readlane_b32 s3, v243, 4
	s_cbranch_scc1 .LBB0_1202
.LBB0_1167:
	s_bfe_u32 s70, s11, 0x20006
	s_lshl_b32 s71, s11, 7
	s_and_b32 s71, s71, 0x1f80
	s_lshl_b32 s72, s11, 5
	s_and_b32 s72, s72, 0xffffe000
	v_readlane_b32 s74, v243, 56
	v_readlane_b32 s75, v243, 57
	s_cmp_eq_u32 s71, 0
	s_cselect_b32 s73, 0, 0xffffff80
	s_or_b32 s72, s72, s71
	s_add_i32 s72, s72, s73
	s_lshl_b32 s70, s70, 7
	s_mov_b32 s71, 0
	s_movk_i32 s78, 0xc00
	v_add_u32_e32 v220, s72, v177
	v_mov_b64_e32 v[222:223], s[74:75]
	s_nop 0
	v_mad_i64_i32 v[220:221], s[76:77], v220, s78, v[222:223]
	v_lshl_add_u64 v[220:221], v[220:221], 0, s[70:71]
	v_lshl_add_u64 v[220:221], v[220:221], 0, v[144:145]
	global_load_dwordx4 v[204:207], v[220:221], off offset:2064
	global_load_dwordx4 v[208:211], v[220:221], off offset:2048
	global_load_dwordx4 v[212:215], v[220:221], off offset:2560
	global_load_dwordx4 v[216:219], v[220:221], off offset:2576
	s_bfe_u32 s1, s11, 0x20006
	s_lshl_b32 s0, s11, 7
	v_lshl_add_u32 v164, s1, 2, v175
	v_readlane_b32 s76, v243, 29
	v_readlane_b32 s77, v243, 30
	v_mov_b32_e32 v240, v164
	v_ashrrev_i32_e32 v241, 31, v164
	s_nop 1
	v_lshl_add_u64 v[240:241], v[240:241], 2, s[76:77]
	global_load_dword v240, v[240:241], off
	s_and_b32 s0, s0, 0x1f80
	s_lshl_b32 s2, s11, 5
	v_lshlrev_b32_e32 v162, 6, v164
	v_or_b32_e32 v18, s0, v176
	s_and_b32 s2, s2, 0xffffe000
	v_ashrrev_i32_e32 v163, 31, v162
	v_lshl_add_u64 v[64:65], v[162:163], 1, v[146:147]
	v_or3_b32 v160, s2, v149, v18
	s_movk_i32 s10, 0xc00
	v_mov_b32_e32 v16, v174
	v_lshrrev_b32_e32 v48, 6, v18
	v_mad_i64_i32 v[18:19], s[4:5], v160, s10, v[64:65]
	global_load_dwordx4 v[84:87], v[18:19], off
	global_load_dwordx4 v[88:91], v[18:19], off offset:32
	global_load_dwordx4 v[94:97], v[18:19], off offset:64
	global_load_dwordx4 v[98:101], v[18:19], off offset:96
	v_lshlrev_b32_e32 v60, 3, v16
	v_ashrrev_i32_e32 v61, 31, v60
	v_lshl_add_u64 v[16:17], v[60:61], 2, s[12:13]
	global_load_dwordx4 v[44:47], v[16:17], off
	global_load_dwordx4 v[40:43], v[16:17], off offset:16
	global_load_dwordx4 v[36:39], v[16:17], off offset:64
	global_load_dwordx4 v[32:35], v[16:17], off offset:80
	v_cvt_f32_i32_e32 v18, v60
	v_or_b32_e32 v51, 2, v60
	v_cvt_f32_i32_e32 v51, v51
	v_cvt_f32_ubyte0_e32 v61, v48
	v_mul_f32_e32 v18, 0xbf549a78, v18
	v_exp_f32_e32 v49, v18
	global_load_dwordx4 v[28:31], v[16:17], off offset:128
	global_load_dwordx4 v[24:27], v[16:17], off offset:144
	global_load_dwordx4 v[20:23], v[16:17], off offset:192
	s_nop 0
	global_load_dwordx4 v[16:19], v[16:17], off offset:208
	v_mul_f32_e32 v51, 0xbf549a78, v51
	v_exp_f32_e32 v53, v51
	v_mul_f32_e32 v165, 0.15915494, v49
	v_or_b32_e32 v49, 1, v60
	v_cvt_f32_i32_e32 v49, v49
	v_or_b32_e32 v57, 5, v60
	v_cvt_f32_i32_e32 v57, v57
	v_mul_f32_e32 v171, 0.15915494, v53
	v_mul_f32_e32 v49, 0xbf549a78, v49
	v_exp_f32_e32 v49, v49
	v_mul_f32_e32 v53, v171, v61
	v_mul_f32_e32 v57, 0xbf549a78, v57
	v_or_b32_e32 v59, 6, v60
	v_mul_f32_e32 v170, 0.15915494, v49
	v_mul_f32_e32 v52, v170, v61
	v_cos_f32_e32 v49, v52
	v_sin_f32_e32 v51, v52
	v_or_b32_e32 v52, 3, v60
	v_cvt_f32_i32_e32 v54, v52
	v_cos_f32_e32 v52, v53
	v_exp_f32_e32 v57, v57
	v_cvt_f32_i32_e32 v59, v59
	v_mul_f32_e32 v54, 0xbf549a78, v54
	v_exp_f32_e32 v55, v54
	v_sin_f32_e32 v54, v53
	v_or_b32_e32 v53, 4, v60
	v_cvt_f32_i32_e32 v56, v53
	v_mul_f32_e32 v187, 0.15915494, v57
	v_mul_f32_e32 v57, 0xbf549a78, v59
	v_exp_f32_e32 v63, v57
	v_mul_f32_e32 v56, 0xbf549a78, v56
	v_exp_f32_e32 v56, v56
	v_or_b32_e32 v57, 7, v60
	v_cvt_f32_i32_e32 v60, v57
	v_mul_f32_e32 v50, v165, v61
	v_mul_f32_e32 v172, 0.15915494, v55
	v_cos_f32_e32 v48, v50
	v_sin_f32_e32 v50, v50
	v_mul_f32_e32 v55, v172, v61
	v_mul_f32_e32 v173, 0.15915494, v56
	v_cos_f32_e32 v53, v55
	v_sin_f32_e32 v55, v55
	v_mul_f32_e32 v58, v173, v61
	v_mul_f32_e32 v62, v187, v61
	v_cos_f32_e32 v56, v58
	v_sin_f32_e32 v58, v58
	v_cos_f32_e32 v57, v62
	v_sin_f32_e32 v59, v62
	v_mul_f32_e32 v60, 0xbf549a78, v60
	v_mul_f32_e32 v92, 0.15915494, v63
	v_exp_f32_e32 v63, v60
	v_or_b32_e32 v166, 32, v160
	v_mad_i64_i32 v[64:65], s[4:5], v166, s10, v[64:65]
	v_mul_f32_e32 v93, 0.15915494, v63
	v_mul_f32_e32 v62, v92, v61
	v_mul_f32_e32 v63, v93, v61
	v_cos_f32_e32 v60, v62
	v_cos_f32_e32 v61, v63
	v_sin_f32_e32 v62, v62
	v_sin_f32_e32 v63, v63
	v_mul_f32_e32 v67, v165, v181
	v_mul_f32_e32 v68, v170, v181
	v_cos_f32_e32 v66, v67
	v_sin_f32_e32 v70, v67
	s_waitcnt vmcnt(11)
	v_lshlrev_b32_e32 v140, 16, v84
	v_and_b32_e32 v141, 0xffff0000, v84
	v_lshlrev_b32_e32 v132, 16, v85
	v_and_b32_e32 v133, 0xffff0000, v85
	v_pk_mul_f32 v[84:85], v[140:141], v[140:141]
	v_pk_mul_f32 v[134:135], v[132:133], v[132:133]
	v_add_f32_e32 v84, v84, v85
	v_lshlrev_b32_e32 v128, 16, v86
	v_and_b32_e32 v129, 0xffff0000, v86
	v_add_f32_e32 v84, v134, v84
	v_lshlrev_b32_e32 v120, 16, v87
	v_and_b32_e32 v121, 0xffff0000, v87
	v_pk_mul_f32 v[86:87], v[128:129], v[128:129]
	v_add_f32_e32 v84, v135, v84
	v_add_f32_e32 v84, v86, v84
	v_pk_mul_f32 v[122:123], v[120:121], v[120:121]
	v_add_f32_e32 v84, v87, v84
	s_waitcnt vmcnt(10)
	v_lshlrev_b32_e32 v142, 16, v88
	v_and_b32_e32 v143, 0xffff0000, v88
	v_add_f32_e32 v84, v122, v84
	v_lshlrev_b32_e32 v136, 16, v89
	v_and_b32_e32 v137, 0xffff0000, v89
	v_pk_mul_f32 v[88:89], v[142:143], v[142:143]
	v_add_f32_e32 v84, v123, v84
	v_add_f32_e32 v84, v88, v84
	v_pk_mul_f32 v[138:139], v[136:137], v[136:137]
	v_add_f32_e32 v84, v89, v84
	v_lshlrev_b32_e32 v130, 16, v90
	v_and_b32_e32 v131, 0xffff0000, v90
	v_add_f32_e32 v84, v138, v84
	v_lshlrev_b32_e32 v124, 16, v91
	v_and_b32_e32 v125, 0xffff0000, v91
	v_pk_mul_f32 v[90:91], v[130:131], v[130:131]
	v_add_f32_e32 v84, v139, v84
	v_add_f32_e32 v84, v90, v84
	v_pk_mul_f32 v[126:127], v[124:125], v[124:125]
	v_add_f32_e32 v84, v91, v84
	s_waitcnt vmcnt(9)
	v_lshlrev_b32_e32 v114, 16, v94
	v_and_b32_e32 v115, 0xffff0000, v94
	v_add_f32_e32 v84, v126, v84
	v_lshlrev_b32_e32 v108, 16, v95
	v_and_b32_e32 v109, 0xffff0000, v95
	v_pk_mul_f32 v[94:95], v[114:115], v[114:115]
	v_add_f32_e32 v84, v127, v84
	v_add_f32_e32 v84, v94, v84
	v_pk_mul_f32 v[110:111], v[108:109], v[108:109]
	v_add_f32_e32 v84, v95, v84
	v_lshlrev_b32_e32 v106, 16, v96
	v_and_b32_e32 v107, 0xffff0000, v96
	v_add_f32_e32 v84, v110, v84
	v_lshlrev_b32_e32 v80, 16, v97
	v_and_b32_e32 v81, 0xffff0000, v97
	v_pk_mul_f32 v[96:97], v[106:107], v[106:107]
	v_add_f32_e32 v84, v111, v84
	v_add_f32_e32 v84, v96, v84
	v_pk_mul_f32 v[102:103], v[80:81], v[80:81]
	v_add_f32_e32 v84, v97, v84
	s_waitcnt vmcnt(8)
	v_lshlrev_b32_e32 v118, 16, v98
	v_and_b32_e32 v119, 0xffff0000, v98
	v_add_f32_e32 v84, v102, v84
	v_lshlrev_b32_e32 v116, 16, v99
	v_and_b32_e32 v117, 0xffff0000, v99
	v_pk_mul_f32 v[98:99], v[118:119], v[118:119]
	v_add_f32_e32 v84, v103, v84
	v_add_f32_e32 v84, v98, v84
	v_pk_mul_f32 v[112:113], v[116:117], v[116:117]
	v_add_f32_e32 v84, v99, v84
	v_lshlrev_b32_e32 v82, 16, v100
	v_and_b32_e32 v83, 0xffff0000, v100
	v_add_f32_e32 v84, v112, v84
	v_lshlrev_b32_e32 v78, 16, v101
	v_and_b32_e32 v79, 0xffff0000, v101
	v_pk_mul_f32 v[100:101], v[82:83], v[82:83]
	v_add_f32_e32 v84, v113, v84
	v_add_f32_e32 v84, v100, v84
	v_pk_mul_f32 v[104:105], v[78:79], v[78:79]
	v_add_f32_e32 v84, v101, v84
	v_add_f32_e32 v84, v104, v84
	v_add_f32_e32 v85, v105, v84
	ds_bpermute_b32 v87, v202, v85
	v_cos_f32_e32 v67, v68
	v_sin_f32_e32 v71, v68
	v_mul_f32_e32 v69, v171, v181
	v_mul_f32_e32 v72, v172, v181
	s_waitcnt lgkmcnt(0)
	v_add_f32_e32 v85, v85, v87
	v_fmamk_f32 v85, v85, 0x3c800000, v186
	v_rsq_f32_e32 v88, v85
	v_cos_f32_e32 v68, v69
	v_sin_f32_e32 v74, v69
	v_cos_f32_e32 v69, v72
	v_mul_f32_e32 v94, 0x3e38aa3b, v88
	s_waitcnt vmcnt(7)
	v_pk_mul_f32 v[88:89], v[44:45], v[94:95] op_sel_hi:[1,0]
	s_waitcnt vmcnt(1)
	v_pk_mul_f32 v[122:123], v[20:21], v[94:95] op_sel_hi:[1,0]
	v_pk_mul_f32 v[96:97], v[88:89], v[140:141]
	v_pk_mul_f32 v[88:89], v[46:47], v[94:95] op_sel_hi:[1,0]
	v_pk_mul_f32 v[112:113], v[26:27], v[94:95] op_sel_hi:[1,0]
	v_pk_mul_f32 v[98:99], v[88:89], v[132:133]
	v_pk_mul_f32 v[88:89], v[40:41], v[94:95] op_sel_hi:[1,0]
	v_pk_mul_f32 v[80:81], v[112:113], v[80:81]
	v_pk_mul_f32 v[100:101], v[88:89], v[128:129]
	v_pk_mul_f32 v[88:89], v[42:43], v[94:95] op_sel_hi:[1,0]
	v_pk_mul_f32 v[128:129], v[122:123], v[118:119]
	v_pk_mul_f32 v[102:103], v[88:89], v[120:121]
	v_pk_mul_f32 v[88:89], v[36:37], v[94:95] op_sel_hi:[1,0]
	v_pk_mul_f32 v[118:119], v[22:23], v[94:95] op_sel_hi:[1,0]
	v_pk_mul_f32 v[104:105], v[88:89], v[142:143]
	v_pk_mul_f32 v[88:89], v[38:39], v[94:95] op_sel_hi:[1,0]
	v_sin_f32_e32 v75, v72
	v_pk_mul_f32 v[110:111], v[88:89], v[136:137]
	v_pk_mul_f32 v[88:89], v[32:33], v[94:95] op_sel_hi:[1,0]
	v_mul_f32_e32 v73, v173, v181
	v_pk_mul_f32 v[120:121], v[88:89], v[130:131]
	v_pk_mul_f32 v[88:89], v[34:35], v[94:95] op_sel_hi:[1,0]
	v_pk_mul_f32 v[130:131], v[118:119], v[116:117]
	v_pk_mul_f32 v[124:125], v[88:89], v[124:125]
	v_pk_mul_f32 v[88:89], v[28:29], v[94:95] op_sel_hi:[1,0]
	s_waitcnt vmcnt(0)
	v_pk_mul_f32 v[116:117], v[16:17], v[94:95] op_sel_hi:[1,0]
	v_pk_mul_f32 v[126:127], v[88:89], v[114:115]
	v_pk_mul_f32 v[88:89], v[30:31], v[94:95] op_sel_hi:[1,0]
	v_pk_mul_f32 v[82:83], v[116:117], v[82:83]
	v_pk_mul_f32 v[108:109], v[88:89], v[108:109]
	v_pk_mul_f32 v[88:89], v[24:25], v[94:95] op_sel_hi:[1,0]
	v_pk_mul_f32 v[94:95], v[18:19], v[94:95] op_sel_hi:[1,0]
	v_pk_mul_f32 v[116:117], v[58:59], v[120:121]
	v_pk_mul_f32 v[78:79], v[94:95], v[78:79]
	v_pk_mul_f32 v[94:95], v[48:49], v[104:105]
	v_pk_mul_f32 v[104:105], v[50:51], v[104:105]
	v_pk_fma_f32 v[94:95], v[50:51], v[96:97], v[94:95]
	v_pk_fma_f32 v[96:97], v[48:49], v[96:97], v[104:105] neg_lo:[0,0,1] neg_hi:[0,0,1]
	v_pk_mul_f32 v[104:105], v[52:53], v[110:111]
	v_pk_mul_f32 v[110:111], v[54:55], v[110:111]
	v_pk_fma_f32 v[104:105], v[54:55], v[98:99], v[104:105]
	v_pk_fma_f32 v[98:99], v[52:53], v[98:99], v[110:111] neg_lo:[0,0,1] neg_hi:[0,0,1]
	v_pk_mul_f32 v[110:111], v[56:57], v[120:121]
	v_pk_mul_f32 v[120:121], v[60:61], v[124:125]
	v_pk_fma_f32 v[110:111], v[58:59], v[100:101], v[110:111]
	v_pk_fma_f32 v[100:101], v[56:57], v[100:101], v[116:117] neg_lo:[0,0,1] neg_hi:[0,0,1]
	global_load_dwordx4 v[116:119], v[64:65], off
	v_pk_fma_f32 v[132:133], v[62:63], v[102:103], v[120:121]
	global_load_dwordx4 v[120:123], v[64:65], off offset:32
	v_pk_mul_f32 v[106:107], v[88:89], v[106:107]
	global_load_dwordx4 v[88:91], v[64:65], off offset:64
	global_load_dwordx4 v[112:115], v[64:65], off offset:96
	v_pk_mul_f32 v[64:65], v[62:63], v[124:125]
	v_mul_f32_e32 v77, v187, v181
	v_pk_fma_f32 v[64:65], v[60:61], v[102:103], v[64:65] neg_lo:[0,0,1] neg_hi:[0,0,1]
	v_pk_mul_f32 v[102:103], v[66:67], v[128:129]
	v_cos_f32_e32 v72, v73
	v_pk_fma_f32 v[124:125], v[70:71], v[126:127], v[102:103]
	v_pk_mul_f32 v[70:71], v[70:71], v[128:129]
	v_sin_f32_e32 v76, v73
	v_pk_fma_f32 v[66:67], v[66:67], v[126:127], v[70:71] neg_lo:[0,0,1] neg_hi:[0,0,1]
	v_pk_mul_f32 v[70:71], v[68:69], v[130:131]
	v_cos_f32_e32 v73, v77
	v_pk_fma_f32 v[70:71], v[74:75], v[108:109], v[70:71]
	v_pk_mul_f32 v[74:75], v[74:75], v[130:131]
	v_sin_f32_e32 v77, v77
	v_pk_fma_f32 v[68:69], v[68:69], v[108:109], v[74:75] neg_lo:[0,0,1] neg_hi:[0,0,1]
	v_cvt_pk_bf16_f32 v109, v70, v71
	v_mul_f32_e32 v70, v172, v182
	v_mul_f32_e32 v71, v173, v182
	v_mul_f32_e32 v86, v92, v181
	v_mul_f32_e32 v87, v93, v181
	v_cos_f32_e32 v84, v86
	v_sin_f32_e32 v86, v86
	v_cos_f32_e32 v85, v87
	v_sin_f32_e32 v87, v87
	v_pk_mul_f32 v[74:75], v[72:73], v[82:83]
	v_cvt_pk_bf16_f32 v96, v96, v97
	v_cvt_pk_bf16_f32 v97, v98, v99
	v_cvt_pk_bf16_f32 v98, v100, v101
	v_cvt_pk_bf16_f32 v101, v104, v105
	v_cvt_pk_bf16_f32 v104, v66, v67
	v_mul_f32_e32 v66, v170, v182
	v_mul_f32_e32 v67, v171, v182
	v_pk_fma_f32 v[74:75], v[76:77], v[106:107], v[74:75]
	v_pk_mul_f32 v[76:77], v[76:77], v[82:83]
	v_cvt_pk_bf16_f32 v103, v132, v133
	v_pk_fma_f32 v[72:73], v[72:73], v[106:107], v[76:77] neg_lo:[0,0,1] neg_hi:[0,0,1]
	v_pk_mul_f32 v[76:77], v[84:85], v[78:79]
	v_pk_mul_f32 v[78:79], v[86:87], v[78:79]
	v_pk_fma_f32 v[76:77], v[86:87], v[80:81], v[76:77]
	v_pk_fma_f32 v[78:79], v[84:85], v[80:81], v[78:79] neg_lo:[0,0,1] neg_hi:[0,0,1]
	v_cvt_pk_bf16_f32 v100, v94, v95
	v_cvt_pk_bf16_f32 v107, v78, v79
	v_cvt_pk_bf16_f32 v102, v110, v111
	v_cvt_pk_bf16_f32 v111, v76, v77
	v_cvt_pk_bf16_f32 v108, v124, v125
	s_cmp_eq_u32 s0, 0
	s_cselect_b64 s[4:5], -1, 0
	v_cvt_pk_bf16_f32 v99, v64, v65
	v_mul_f32_e32 v65, v165, v182
	v_cndmask_b32_e64 v165, 0, 1, s[4:5]
	s_and_b64 s[4:5], s[4:5], exec
	s_cselect_b32 s3, 0, 0xffffff80
	s_or_b32 s24, s2, s0
	s_add_i32 s4, s3, s24
	v_readlane_b32 s2, v243, 56
	v_readlane_b32 s3, v243, 57
	s_lshl_b32 s6, s1, 7
	s_barrier
	v_cvt_pk_bf16_f32 v105, v68, v69
	v_cos_f32_e32 v64, v65
	v_sin_f32_e32 v68, v65
	v_cos_f32_e32 v65, v66
	v_sin_f32_e32 v69, v66
	v_cvt_pk_bf16_f32 v106, v72, v73
	v_cvt_pk_bf16_f32 v110, v74, v75
	v_cos_f32_e32 v66, v67
	v_sin_f32_e32 v72, v67
	v_cos_f32_e32 v67, v70
	v_sin_f32_e32 v73, v70
	v_mul_f32_e32 v75, v187, v182
	v_cos_f32_e32 v70, v71
	v_sin_f32_e32 v74, v71
	s_waitcnt vmcnt(3)
	v_lshlrev_b32_e32 v194, 16, v116
	v_and_b32_e32 v195, 0xffff0000, v116
	v_lshlrev_b32_e32 v172, 16, v117
	v_and_b32_e32 v173, 0xffff0000, v117
	v_pk_mul_f32 v[116:117], v[194:195], v[194:195]
	v_pk_mul_f32 v[188:189], v[172:173], v[172:173]
	v_add_f32_e32 v116, v116, v117
	v_lshlrev_b32_e32 v142, 16, v118
	v_and_b32_e32 v143, 0xffff0000, v118
	v_add_f32_e32 v116, v188, v116
	v_lshlrev_b32_e32 v134, 16, v119
	v_and_b32_e32 v135, 0xffff0000, v119
	v_pk_mul_f32 v[118:119], v[142:143], v[142:143]
	v_add_f32_e32 v116, v189, v116
	v_add_f32_e32 v116, v118, v116
	v_pk_mul_f32 v[136:137], v[134:135], v[134:135]
	v_add_f32_e32 v116, v119, v116
	s_waitcnt vmcnt(2)
	v_lshlrev_b32_e32 v196, 16, v120
	v_and_b32_e32 v197, 0xffff0000, v120
	v_add_f32_e32 v116, v136, v116
	v_lshlrev_b32_e32 v190, 16, v121
	v_and_b32_e32 v191, 0xffff0000, v121
	v_pk_mul_f32 v[120:121], v[196:197], v[196:197]
	v_add_f32_e32 v116, v137, v116
	v_add_f32_e32 v116, v120, v116
	v_pk_mul_f32 v[192:193], v[190:191], v[190:191]
	v_add_f32_e32 v116, v121, v116
	v_lshlrev_b32_e32 v170, 16, v122
	v_and_b32_e32 v171, 0xffff0000, v122
	v_add_f32_e32 v116, v192, v116
	v_lshlrev_b32_e32 v138, 16, v123
	v_and_b32_e32 v139, 0xffff0000, v123
	v_pk_mul_f32 v[122:123], v[170:171], v[170:171]
	v_add_f32_e32 v116, v193, v116
	v_add_f32_e32 v116, v122, v116
	v_pk_mul_f32 v[140:141], v[138:139], v[138:139]
	v_add_f32_e32 v116, v123, v116
	s_waitcnt vmcnt(1)
	v_lshlrev_b32_e32 v78, 16, v91
	v_and_b32_e32 v79, 0xffff0000, v91
	v_lshlrev_b32_e32 v82, 16, v90
	v_and_b32_e32 v83, 0xffff0000, v90
	v_lshlrev_b32_e32 v90, 16, v88
	v_and_b32_e32 v91, 0xffff0000, v88
	v_add_f32_e32 v116, v140, v116
	v_pk_mul_f32 v[132:133], v[90:91], v[90:91]
	v_add_f32_e32 v116, v141, v116
	v_lshlrev_b32_e32 v86, 16, v89
	v_and_b32_e32 v87, 0xffff0000, v89
	v_add_f32_e32 v116, v132, v116
	v_pk_mul_f32 v[128:129], v[86:87], v[86:87]
	v_add_f32_e32 v116, v133, v116
	v_add_f32_e32 v116, v128, v116
	v_pk_mul_f32 v[126:127], v[82:83], v[82:83]
	v_add_f32_e32 v116, v129, v116
	v_add_f32_e32 v116, v126, v116
	v_pk_mul_f32 v[94:95], v[78:79], v[78:79]
	v_add_f32_e32 v116, v127, v116
	s_waitcnt vmcnt(0)
	v_lshlrev_b32_e32 v88, 16, v112
	v_and_b32_e32 v89, 0xffff0000, v112
	v_add_f32_e32 v94, v94, v116
	v_lshlrev_b32_e32 v84, 16, v113
	v_and_b32_e32 v85, 0xffff0000, v113
	v_pk_mul_f32 v[112:113], v[88:89], v[88:89]
	v_add_f32_e32 v94, v95, v94
	v_add_f32_e32 v94, v112, v94
	v_pk_mul_f32 v[130:131], v[84:85], v[84:85]
	v_add_f32_e32 v94, v113, v94
	v_lshlrev_b32_e32 v80, 16, v114
	v_and_b32_e32 v81, 0xffff0000, v114
	v_add_f32_e32 v94, v130, v94
	v_lshlrev_b32_e32 v76, 16, v115
	v_and_b32_e32 v77, 0xffff0000, v115
	v_pk_mul_f32 v[114:115], v[80:81], v[80:81]
	v_add_f32_e32 v94, v131, v94
	v_add_f32_e32 v94, v114, v94
	v_pk_mul_f32 v[124:125], v[76:77], v[76:77]
	v_add_f32_e32 v94, v115, v94
	v_add_f32_e32 v94, v124, v94
	v_add_f32_e32 v95, v125, v94
	ds_bpermute_b32 v112, v202, v95
	v_mov_b64_e32 v[120:121], s[2:3]
	v_or_b32_e32 v122, s4, v148
	v_cos_f32_e32 v71, v75
	v_sin_f32_e32 v75, v75
	s_waitcnt lgkmcnt(0)
	v_add_f32_e32 v95, v95, v112
	v_fmamk_f32 v95, v95, 0x3c800000, v186
	v_rsq_f32_e32 v112, v95
	v_mul_f32_e32 v94, v92, v182
	v_mul_f32_e32 v95, v93, v182
	v_cos_f32_e32 v92, v94
	v_mul_f32_e32 v128, 0x3e38aa3b, v112
	v_add_u32_e32 v112, s4, v177
	v_mad_i64_i32 v[112:113], s[2:3], v112, s10, v[120:121]
	v_mad_i64_i32 v[120:121], s[2:3], v122, s10, v[120:121]
	v_lshl_add_u64 v[112:113], v[112:113], 0, s[6:7]
	v_lshl_add_u64 v[120:121], v[120:121], 0, s[6:7]
	v_lshl_add_u64 v[116:117], v[112:113], 0, v[144:145]
	v_lshl_add_u64 v[124:125], v[112:113], 0, v[144:145]
	s_nop 0
	s_nop 0
	s_nop 0
	v_pk_mul_f32 v[36:37], v[36:37], v[128:129] op_sel_hi:[1,0]
	s_nop 0
	v_pk_mul_f32 v[44:45], v[44:45], v[128:129] op_sel_hi:[1,0]
	s_nop 0
	v_pk_mul_f32 v[36:37], v[36:37], v[196:197]
	v_pk_mul_f32 v[38:39], v[38:39], v[128:129] op_sel_hi:[1,0]
	v_pk_mul_f32 v[18:19], v[18:19], v[128:129] op_sel_hi:[1,0]
	v_pk_mul_f32 v[44:45], v[44:45], v[194:195]
	v_pk_mul_f32 v[46:47], v[46:47], v[128:129] op_sel_hi:[1,0]
	v_pk_mul_f32 v[38:39], v[38:39], v[190:191]
	v_pk_mul_f32 v[32:33], v[32:33], v[128:129] op_sel_hi:[1,0]
	v_pk_mul_f32 v[18:19], v[18:19], v[76:77]
	v_pk_mul_f32 v[76:77], v[48:49], v[36:37]
	v_pk_mul_f32 v[36:37], v[50:51], v[36:37]
	v_pk_mul_f32 v[46:47], v[46:47], v[172:173]
	v_pk_mul_f32 v[40:41], v[40:41], v[128:129] op_sel_hi:[1,0]
	v_pk_mul_f32 v[32:33], v[32:33], v[170:171]
	v_pk_mul_f32 v[34:35], v[34:35], v[128:129] op_sel_hi:[1,0]
	v_pk_fma_f32 v[76:77], v[50:51], v[44:45], v[76:77]
	v_pk_fma_f32 v[36:37], v[48:49], v[44:45], v[36:37] neg_lo:[0,0,1] neg_hi:[0,0,1]
	v_pk_mul_f32 v[44:45], v[52:53], v[38:39]
	v_pk_mul_f32 v[38:39], v[54:55], v[38:39]
	v_pk_mul_f32 v[40:41], v[40:41], v[142:143]
	v_pk_mul_f32 v[42:43], v[42:43], v[128:129] op_sel_hi:[1,0]
	v_pk_mul_f32 v[34:35], v[34:35], v[138:139]
	v_pk_mul_f32 v[20:21], v[20:21], v[128:129] op_sel_hi:[1,0]
	v_pk_fma_f32 v[44:45], v[54:55], v[46:47], v[44:45]
	v_pk_fma_f32 v[38:39], v[52:53], v[46:47], v[38:39] neg_lo:[0,0,1] neg_hi:[0,0,1]
	v_pk_mul_f32 v[46:47], v[56:57], v[32:33]
	v_pk_mul_f32 v[32:33], v[58:59], v[32:33]
	v_sin_f32_e32 v94, v94
	v_cos_f32_e32 v93, v95
	v_sin_f32_e32 v95, v95
	v_pk_mul_f32 v[42:43], v[42:43], v[134:135]
	v_pk_mul_f32 v[28:29], v[28:29], v[128:129] op_sel_hi:[1,0]
	v_pk_mul_f32 v[20:21], v[20:21], v[88:89]
	v_pk_mul_f32 v[22:23], v[22:23], v[128:129] op_sel_hi:[1,0]
	v_pk_fma_f32 v[46:47], v[58:59], v[40:41], v[46:47]
	v_pk_fma_f32 v[32:33], v[56:57], v[40:41], v[32:33] neg_lo:[0,0,1] neg_hi:[0,0,1]
	v_pk_mul_f32 v[40:41], v[60:61], v[34:35]
	v_pk_mul_f32 v[34:35], v[62:63], v[34:35]
	v_pk_mul_f32 v[28:29], v[28:29], v[90:91]
	v_pk_mul_f32 v[30:31], v[30:31], v[128:129] op_sel_hi:[1,0]
	v_pk_mul_f32 v[22:23], v[22:23], v[84:85]
	v_pk_mul_f32 v[16:17], v[16:17], v[128:129] op_sel_hi:[1,0]
	v_pk_fma_f32 v[40:41], v[62:63], v[42:43], v[40:41]
	v_pk_fma_f32 v[34:35], v[60:61], v[42:43], v[34:35] neg_lo:[0,0,1] neg_hi:[0,0,1]
	v_pk_mul_f32 v[42:43], v[64:65], v[20:21]
	v_pk_mul_f32 v[20:21], v[68:69], v[20:21]
	v_pk_mul_f32 v[30:31], v[30:31], v[86:87]
	v_pk_mul_f32 v[24:25], v[24:25], v[128:129] op_sel_hi:[1,0]
	v_pk_mul_f32 v[16:17], v[16:17], v[80:81]
	v_pk_fma_f32 v[42:43], v[68:69], v[28:29], v[42:43]
	v_pk_fma_f32 v[20:21], v[64:65], v[28:29], v[20:21] neg_lo:[0,0,1] neg_hi:[0,0,1]
	v_pk_mul_f32 v[28:29], v[66:67], v[22:23]
	v_pk_mul_f32 v[22:23], v[72:73], v[22:23]
	v_pk_mul_f32 v[24:25], v[24:25], v[82:83]
	v_pk_mul_f32 v[26:27], v[26:27], v[128:129] op_sel_hi:[1,0]
	v_pk_fma_f32 v[28:29], v[72:73], v[30:31], v[28:29]
	v_pk_fma_f32 v[22:23], v[66:67], v[30:31], v[22:23] neg_lo:[0,0,1] neg_hi:[0,0,1]
	v_pk_mul_f32 v[30:31], v[70:71], v[16:17]
	v_pk_mul_f32 v[16:17], v[74:75], v[16:17]
	v_pk_mul_f32 v[26:27], v[26:27], v[78:79]
	v_pk_fma_f32 v[30:31], v[74:75], v[24:25], v[30:31]
	v_pk_fma_f32 v[16:17], v[70:71], v[24:25], v[16:17] neg_lo:[0,0,1] neg_hi:[0,0,1]
	v_pk_mul_f32 v[24:25], v[92:93], v[18:19]
	v_pk_mul_f32 v[18:19], v[94:95], v[18:19]
	v_pk_fma_f32 v[24:25], v[94:95], v[26:27], v[24:25]
	v_pk_fma_f32 v[18:19], v[92:93], v[26:27], v[18:19] neg_lo:[0,0,1] neg_hi:[0,0,1]
	v_cvt_pk_bf16_f32 v142, v30, v31
	s_cmpk_eq_i32 s0, 0x1f80
	v_mov_b32_e32 v30, v145
	v_mov_b32_e32 v31, v145
	v_cvt_pk_bf16_f32 v128, v36, v37
	v_cvt_pk_bf16_f32 v129, v38, v39
	v_cvt_pk_bf16_f32 v130, v32, v33
	v_cvt_pk_bf16_f32 v131, v34, v35
	v_cvt_pk_bf16_f32 v132, v76, v77
	v_cvt_pk_bf16_f32 v133, v44, v45
	v_cvt_pk_bf16_f32 v134, v46, v47
	v_cvt_pk_bf16_f32 v135, v40, v41
	v_cvt_pk_bf16_f32 v136, v20, v21
	v_cvt_pk_bf16_f32 v137, v22, v23
	v_cvt_pk_bf16_f32 v138, v16, v17
	v_cvt_pk_bf16_f32 v139, v18, v19
	v_cvt_pk_bf16_f32 v140, v42, v43
	v_cvt_pk_bf16_f32 v141, v28, v29
	v_cvt_pk_bf16_f32 v143, v24, v25
	s_cselect_b32 s22, 3, 2
	v_writelane_b32 v243, s11, 60
	s_and_b32 s23, s11, 0xffffff00
	s_mov_b32 s1, s7
	v_mov_b32_e32 v16, v145
	v_mov_b32_e32 v17, v145
	v_mov_b32_e32 v18, v145
	v_mov_b32_e32 v19, v145
	v_mov_b32_e32 v20, v145
	v_mov_b32_e32 v21, v145
	v_mov_b32_e32 v22, v145
	v_mov_b32_e32 v23, v145
	v_mov_b32_e32 v24, v145
	v_mov_b32_e32 v25, v145
	v_mov_b32_e32 v26, v145
	v_mov_b32_e32 v27, v145
	v_mov_b32_e32 v28, v145
	v_mov_b32_e32 v29, v145
	v_mov_b64_e32 v[46:47], v[30:31]
	v_mov_b64_e32 v[62:63], v[30:31]
	v_mov_b64_e32 v[78:79], v[30:31]
	v_ashrrev_i32_e32 v161, 31, v160
	v_ashrrev_i32_e32 v167, 31, v166
	s_mov_b32 s33, 0
	v_readfirstlane_b32 s25, v165
	s_add_i32 s23, s23, 0xfe80
	s_addk_i32 s24, 0xff80
	v_lshl_add_u64 v[170:171], v[156:157], 0, s[6:7]
	v_writelane_b32 v243, s0, 50
	v_lshl_add_u64 v[172:173], v[158:159], 0, s[6:7]
	v_mov_b64_e32 v[44:45], v[28:29]
	v_mov_b64_e32 v[42:43], v[26:27]
	v_mov_b64_e32 v[40:41], v[24:25]
	v_mov_b64_e32 v[38:39], v[22:23]
	v_mov_b64_e32 v[36:37], v[20:21]
	v_mov_b64_e32 v[34:35], v[18:19]
	v_mov_b64_e32 v[32:33], v[16:17]
	v_mov_b64_e32 v[60:61], v[28:29]
	v_mov_b64_e32 v[58:59], v[26:27]
	v_mov_b64_e32 v[56:57], v[24:25]
	v_mov_b64_e32 v[54:55], v[22:23]
	v_mov_b64_e32 v[52:53], v[20:21]
	v_mov_b64_e32 v[50:51], v[18:19]
	v_mov_b64_e32 v[48:49], v[16:17]
	v_mov_b64_e32 v[76:77], v[28:29]
	v_mov_b64_e32 v[74:75], v[26:27]
	v_mov_b64_e32 v[72:73], v[24:25]
	v_mov_b64_e32 v[70:71], v[22:23]
	v_mov_b64_e32 v[68:69], v[20:21]
	v_mov_b64_e32 v[66:67], v[18:19]
	v_mov_b64_e32 v[64:65], v[16:17]
	v_mov_b32_e32 v187, 0
	v_mov_b32_e32 v188, 0
	s_waitcnt vmcnt(2)
	ds_write_b128 v179, v[208:211]
	ds_write_b128 v179, v[204:207] offset:16
	s_waitcnt vmcnt(1)
	ds_write_b16 v153, v212 offset:18432
	ds_write_b16_d16_hi v153, v212 offset:18696
	ds_write_b16 v153, v213 offset:18960
	ds_write_b16_d16_hi v153, v213 offset:19224
	ds_write_b16 v153, v214 offset:19488
	ds_write_b16_d16_hi v153, v214 offset:19752
	ds_write_b16 v153, v215 offset:20016
	ds_write_b16_d16_hi v153, v215 offset:20280
	s_waitcnt vmcnt(0)
	ds_write_b16 v153, v216 offset:20544
	ds_write_b16_d16_hi v153, v216 offset:20808
	ds_write_b16 v153, v217 offset:21072
	ds_write_b16_d16_hi v153, v217 offset:21336
	ds_write_b16 v153, v218 offset:21600
	ds_write_b16_d16_hi v153, v218 offset:21864
	ds_write_b16 v153, v219 offset:22128
	ds_write_b16_d16_hi v153, v219 offset:22392
	s_waitcnt lgkmcnt(0)
	s_barrier
	v_writelane_b32 v243, s1, 51
